# code placement: general sub-tile and everything behind it shifted by 4 bytes (lean tile unchanged)
# baseline (speedup 1.0000x reference)
.LBB0_658:
	s_and_b64 vcc, exec, s[0:1]
	s_cbranch_vccz .LBB0_653
	s_lshl_b32 s0, s76, 14
	s_or_b32 s76, s0, s21
	s_lshl_b32 s77, s77, 6
	s_add_i32 s78, s77, 63
	s_cmp_gt_i32 s78, s72
	s_cbranch_scc1 .Lflt_no
	s_cmp_lt_i32 s77, s71
	s_cbranch_scc1 .Lflt_no
	s_sub_i32 s0, s33, s78
	s_cmpk_gt_i32 s0, 0x7f
	s_cselect_b64 s[0:1], -1, 0
	s_or_b64 s[0:1], s[0:1], s[30:31]
	s_and_b64 vcc, exec, s[0:1]
	s_cbranch_vccz .Lflt_no
	v_add_u32_e32 v3, s76, v198
	ds_read_b128 v[4:7], v3
	v_add_u32_e32 v16, s76, v206
	ds_read_b128 v[8:11], v16
	v_add_u32_e32 v17, s76, v207
	ds_read_b128 v[12:15], v17
	v_add_u32_e32 v238, s76, v208
	ds_read_b128 v[214:217], v238
	ds_read_b128 v[234:237], v3 offset:4096
	ds_read_b128 v[244:247], v16 offset:4096
	ds_read_b128 v[248:251], v17 offset:4096
	ds_read_b128 v[252:255], v238 offset:4096
	s_setprio 1
	s_waitcnt lgkmcnt(7)
	v_mfma_f32_32x32x16_bf16 v[118:133], v[4:7], v[134:137], v[86:101]
	s_waitcnt lgkmcnt(6)
	v_mfma_f32_32x32x16_bf16 v[118:133], v[8:11], v[138:141], v[118:133]
	s_waitcnt lgkmcnt(5)
	v_mfma_f32_32x32x16_bf16 v[118:133], v[12:15], v[142:145], v[118:133]
	s_waitcnt lgkmcnt(4)
	v_mfma_f32_32x32x16_bf16 v[118:133], v[214:217], v[150:153], v[118:133]
	s_add_i32 s0, s76, 0x2000
	v_mfma_f32_32x32x16_bf16 v[102:117], v[4:7], v[146:149], v[86:101]
	v_add_u32_e32 v3, s0, v200
	ds_read_b64_tr_b16 v[4:5], v3 offset:0
	ds_read_b64_tr_b16 v[6:7], v3 offset:1024
	v_mfma_f32_32x32x16_bf16 v[102:117], v[8:11], v[154:157], v[102:117]
	ds_read_b64_tr_b16 v[8:9], v3 offset:2048
	ds_read_b64_tr_b16 v[10:11], v3 offset:3072
	s_nop 4
	v_exp_f32_e32 v118, v118
	v_exp_f32_e32 v119, v119
	v_exp_f32_e32 v120, v120
	v_mfma_f32_32x32x16_bf16 v[102:117], v[12:15], v[158:161], v[102:117]
	v_add_u32_e32 v3, s0, v201
	ds_read_b64_tr_b16 v[12:13], v3 offset:0
	ds_read_b64_tr_b16 v[14:15], v3 offset:1024
	v_exp_f32_e32 v121, v121
	v_exp_f32_e32 v122, v122
	v_exp_f32_e32 v123, v123
	v_mfma_f32_32x32x16_bf16 v[102:117], v[214:217], v[162:165], v[102:117]
	ds_read_b64_tr_b16 v[214:215], v3 offset:2048
	ds_read_b64_tr_b16 v[216:217], v3 offset:3072
	v_exp_f32_e32 v124, v124
	v_exp_f32_e32 v125, v125
	v_exp_f32_e32 v126, v126
	s_waitcnt lgkmcnt(8)
	v_mfma_f32_32x32x16_bf16 v[218:233], v[234:237], v[134:137], v[86:101]
	v_exp_f32_e32 v127, v127
	v_exp_f32_e32 v128, v128
	v_exp_f32_e32 v129, v129
	v_mfma_f32_32x32x16_bf16 v[218:233], v[244:247], v[138:141], v[218:233]
	v_exp_f32_e32 v130, v130
	v_exp_f32_e32 v131, v131
	v_exp_f32_e32 v132, v132
	v_mfma_f32_32x32x16_bf16 v[218:233], v[248:251], v[142:145], v[218:233]
	v_exp_f32_e32 v133, v133
	v_add_f32_e32 v16, v118, v120
	v_add_f32_e32 v17, v119, v121
	v_add_f32_e32 v16, v16, v122
	v_add_f32_e32 v17, v17, v123
	v_add_f32_e32 v16, v16, v124
	v_add_f32_e32 v17, v17, v125
	v_cvt_pk_bf16_f32 v118, v118, v119
	v_cvt_pk_bf16_f32 v119, v120, v121
	v_cvt_pk_bf16_f32 v120, v122, v123
	v_mfma_f32_32x32x16_bf16 v[218:233], v[252:255], v[150:153], v[218:233]
	v_cvt_pk_bf16_f32 v121, v124, v125
	v_cvt_pk_bf16_f32 v122, v126, v127
	v_cvt_pk_bf16_f32 v123, v128, v129
	v_cvt_pk_bf16_f32 v124, v130, v131
	v_cvt_pk_bf16_f32 v125, v132, v133
	v_add_f32_e32 v16, v16, v126
	v_add_f32_e32 v17, v17, v127
	v_add_f32_e32 v16, v16, v128
	v_add_f32_e32 v17, v17, v129
	v_add_f32_e32 v16, v16, v130
	v_add_f32_e32 v17, v17, v131
	v_add_f32_e32 v16, v16, v132
	v_add_f32_e32 v17, v17, v133
	s_waitcnt lgkmcnt(0)
	v_mfma_f32_32x32x16_bf16 v[20:35], v[4:7], v[118:121], v[20:35]
	v_exp_f32_e32 v102, v102
	v_exp_f32_e32 v103, v103
	v_exp_f32_e32 v104, v104
	v_mfma_f32_32x32x16_bf16 v[36:51], v[12:15], v[118:121], v[36:51]
	v_exp_f32_e32 v105, v105
	v_exp_f32_e32 v106, v106
	v_exp_f32_e32 v107, v107
	v_mfma_f32_32x32x16_bf16 v[20:35], v[8:11], v[122:125], v[20:35]
	v_exp_f32_e32 v108, v108
	v_exp_f32_e32 v109, v109
	v_exp_f32_e32 v110, v110
	v_mfma_f32_32x32x16_bf16 v[36:51], v[214:217], v[122:125], v[36:51]
	v_exp_f32_e32 v111, v111
	v_exp_f32_e32 v112, v112
	v_exp_f32_e32 v113, v113
	s_add_i32 s0, s76, 0x3000
	v_mfma_f32_32x32x16_bf16 v[118:133], v[234:237], v[146:149], v[86:101]
	v_add_u32_e32 v3, s0, v200
	ds_read_b64_tr_b16 v[234:235], v3 offset:0
	ds_read_b64_tr_b16 v[236:237], v3 offset:1024
	v_exp_f32_e32 v114, v114
	v_exp_f32_e32 v115, v115
	v_exp_f32_e32 v116, v116
	v_mfma_f32_32x32x16_bf16 v[118:133], v[244:247], v[154:157], v[118:133]
	ds_read_b64_tr_b16 v[244:245], v3 offset:2048
	ds_read_b64_tr_b16 v[246:247], v3 offset:3072
	v_exp_f32_e32 v117, v117
	v_add_f32_e32 v238, v102, v104
	v_add_f32_e32 v239, v103, v105
	v_add_f32_e32 v238, v238, v106
	v_add_f32_e32 v239, v239, v107
	v_add_f32_e32 v238, v238, v108
	v_add_f32_e32 v239, v239, v109
	v_cvt_pk_bf16_f32 v102, v102, v103
	v_cvt_pk_bf16_f32 v103, v104, v105
	v_mfma_f32_32x32x16_bf16 v[118:133], v[248:251], v[158:161], v[118:133]
	v_add_u32_e32 v3, s0, v201
	ds_read_b64_tr_b16 v[248:249], v3 offset:0
	ds_read_b64_tr_b16 v[250:251], v3 offset:1024
	v_cvt_pk_bf16_f32 v104, v106, v107
	v_cvt_pk_bf16_f32 v105, v108, v109
	v_cvt_pk_bf16_f32 v106, v110, v111
	v_cvt_pk_bf16_f32 v107, v112, v113
	v_cvt_pk_bf16_f32 v108, v114, v115
	v_cvt_pk_bf16_f32 v109, v116, v117
	v_mfma_f32_32x32x16_bf16 v[118:133], v[252:255], v[162:165], v[118:133]
	ds_read_b64_tr_b16 v[252:253], v3 offset:2048
	ds_read_b64_tr_b16 v[254:255], v3 offset:3072
	v_add_f32_e32 v238, v238, v110
	v_add_f32_e32 v239, v239, v111
	v_add_f32_e32 v238, v238, v112
	v_add_f32_e32 v239, v239, v113
	v_add_f32_e32 v238, v238, v114
	v_add_f32_e32 v239, v239, v115
	v_add_f32_e32 v238, v238, v116
	v_add_f32_e32 v239, v239, v117
	v_mfma_f32_32x32x16_bf16 v[68:83], v[4:7], v[102:105], v[68:83]
	v_exp_f32_e32 v218, v218
	v_exp_f32_e32 v219, v219
	v_exp_f32_e32 v220, v220
	v_mfma_f32_32x32x16_bf16 v[52:67], v[12:15], v[102:105], v[52:67]
	v_exp_f32_e32 v221, v221
	v_exp_f32_e32 v222, v222
	v_exp_f32_e32 v223, v223
	v_mfma_f32_32x32x16_bf16 v[68:83], v[8:11], v[106:109], v[68:83]
	v_exp_f32_e32 v224, v224
	v_exp_f32_e32 v225, v225
	v_exp_f32_e32 v226, v226
	v_mfma_f32_32x32x16_bf16 v[52:67], v[214:217], v[106:109], v[52:67]
	v_exp_f32_e32 v227, v227
	v_exp_f32_e32 v228, v228
	v_exp_f32_e32 v229, v229
	v_exp_f32_e32 v230, v230
	v_exp_f32_e32 v231, v231
	v_exp_f32_e32 v232, v232
	v_exp_f32_e32 v233, v233
	v_add_f32_e32 v16, v16, v218
	v_add_f32_e32 v17, v17, v219
	v_add_f32_e32 v16, v16, v220
	v_add_f32_e32 v17, v17, v221
	v_add_f32_e32 v16, v16, v222
	v_add_f32_e32 v17, v17, v223
	v_add_f32_e32 v16, v16, v224
	v_add_f32_e32 v17, v17, v225
	v_cvt_pk_bf16_f32 v218, v218, v219
	v_cvt_pk_bf16_f32 v219, v220, v221
	v_cvt_pk_bf16_f32 v220, v222, v223
	v_cvt_pk_bf16_f32 v221, v224, v225
	v_cvt_pk_bf16_f32 v222, v226, v227
	v_cvt_pk_bf16_f32 v223, v228, v229
	v_cvt_pk_bf16_f32 v224, v230, v231
	v_cvt_pk_bf16_f32 v225, v232, v233
	s_waitcnt lgkmcnt(0)
	v_mfma_f32_32x32x16_bf16 v[20:35], v[234:237], v[218:221], v[20:35]
	v_exp_f32_e32 v118, v118
	v_exp_f32_e32 v119, v119
	v_exp_f32_e32 v120, v120
	v_mfma_f32_32x32x16_bf16 v[36:51], v[248:251], v[218:221], v[36:51]
	v_exp_f32_e32 v121, v121
	v_exp_f32_e32 v122, v122
	v_exp_f32_e32 v123, v123
	v_mfma_f32_32x32x16_bf16 v[20:35], v[244:247], v[222:225], v[20:35]
	v_exp_f32_e32 v124, v124
	v_exp_f32_e32 v125, v125
	v_exp_f32_e32 v126, v126
	v_mfma_f32_32x32x16_bf16 v[36:51], v[252:255], v[222:225], v[36:51]
	v_exp_f32_e32 v127, v127
	v_exp_f32_e32 v128, v128
	v_exp_f32_e32 v129, v129
	v_exp_f32_e32 v130, v130
	v_exp_f32_e32 v131, v131
	v_exp_f32_e32 v132, v132
	v_exp_f32_e32 v133, v133
	v_add_f32_e32 v238, v238, v118
	v_add_f32_e32 v239, v239, v119
	v_add_f32_e32 v238, v238, v120
	v_add_f32_e32 v239, v239, v121
	v_add_f32_e32 v238, v238, v122
	v_add_f32_e32 v239, v239, v123
	v_add_f32_e32 v238, v238, v124
	v_add_f32_e32 v239, v239, v125
	v_cvt_pk_bf16_f32 v118, v118, v119
	v_cvt_pk_bf16_f32 v119, v120, v121
	v_cvt_pk_bf16_f32 v120, v122, v123
	v_cvt_pk_bf16_f32 v121, v124, v125
	v_cvt_pk_bf16_f32 v122, v126, v127
	v_cvt_pk_bf16_f32 v123, v128, v129
	v_cvt_pk_bf16_f32 v124, v130, v131
	v_cvt_pk_bf16_f32 v125, v132, v133
	v_mfma_f32_32x32x16_bf16 v[68:83], v[234:237], v[118:121], v[68:83]
	v_add_f32_e32 v16, v16, v226
	v_add_f32_e32 v17, v17, v227
	v_add_f32_e32 v16, v16, v228
	v_add_f32_e32 v17, v17, v229
	v_mfma_f32_32x32x16_bf16 v[52:67], v[248:251], v[118:121], v[52:67]
	v_add_f32_e32 v16, v16, v230
	v_add_f32_e32 v17, v17, v231
	v_add_f32_e32 v16, v16, v232
	v_add_f32_e32 v17, v17, v233
	v_mfma_f32_32x32x16_bf16 v[68:83], v[244:247], v[122:125], v[68:83]
	v_add_f32_e32 v238, v238, v126
	v_add_f32_e32 v239, v239, v127
	v_add_f32_e32 v238, v238, v128
	v_add_f32_e32 v239, v239, v129
	v_mfma_f32_32x32x16_bf16 v[52:67], v[252:255], v[122:125], v[52:67]
	v_add_f32_e32 v238, v238, v130
	v_add_f32_e32 v239, v239, v131
	v_add_f32_e32 v238, v238, v132
	v_add_f32_e32 v239, v239, v133
	s_setprio 0
	v_add_f32_e32 v16, v16, v17
	v_add_f32_e32 v238, v238, v239
	v_add_f32_e32 v180, v180, v16
	v_add_f32_e32 v181, v181, v238
	s_branch .LBB0_653
	s_nop 0
